# v96 + IN plain epilogue line-pair exchange with fused v_cndmask_b32_dpp (8 VALU per row group instead of 24)
# baseline (speedup 1.0000x reference)
; __device__ __forceinline__ unsigned cvtpk_h(float lo, float hi) { f32x2 v = {lo, hi}; h16x2 b = __builtin_convertvector(v, h16x2); return __builtin_bit_cast(unsigned, b); }
; __device__ __forceinline__ void stg_line_pair(void* base, unsigned roA, unsigned rowb, const u32x4 w0, const u32x4 w1, bool odd) {
;     u32x4 a, b;
; #pragma unroll
;     for (int c = 0; c < 4; ++c) { const unsigned p1 = (unsigned)__builtin_amdgcn_update_dpp(0, (int)w1[c], 0xB1, 0xF, 0xF, false), p0 = (unsigned)__builtin_amdgcn_update_dpp(0, (int)w0[c], 0xB1, 0xF, 0xF, false);
;         a[c] = odd ? p1 : w0[c]; b[c] = odd ? w1[c] : p0; }
;     stg_u4(base, roA, a); stg_u4(base, roA + rowb, b);
; }
;     __device__ __forceinline__ void operator()(const f32x4 (&acc)[2][2][4][2], const pg8::Unit& u, int wr, int wc, int fr, int fq) const {
;     ...
;             const bool odd = (fr & 1) != 0;
;             const unsigned offA = base + ((row0 + (unsigned)(wr * 64 + (fr & ~1))) * pitch + coff) * 2u + (odd ? 64u : 0u) + 16u * fq;
; #pragma unroll
;             for (int ai = 0; ai < 2; ++ai)
; #pragma unroll
;                 for (int m = 0; m < 4; ++m) { const unsigned ro = offA + (unsigned)(ai * 8 + m) * rowstep; const float r = rs[ai][m];
;                     u32x4 w[2];
; #pragma unroll
;                     for (int bj = 0; bj < 2; ++bj) { const f32x4 v0 = acc[ai][bj][m][0] * r + bv[bj][0], v1 = acc[ai][bj][m][1] * r + bv[bj][1];
;                         w[bj].x = cvtpk_h(v0[0], v0[1]); w[bj].y = cvtpk_h(v0[2], v0[3]); w[bj].z = cvtpk_h(v1[0], v1[1]); w[bj].w = cvtpk_h(v1[2], v1[3]); }
;                     stg_line_pair(wst, ro, 2u * pitch, w[0], w[1], odd);
;                     asm volatile("" ::: "memory"); }
.LBB0_632:
	v_and_b32_e32 v178, 0x7ffffffe, v202
	s_add_i32 s2, s42, s77
	v_add_u32_e32 v178, s2, v178
	v_and_b32_e32 v186, 1, v202
	v_mul_lo_u32 v178, s9, v178
	v_add_lshl_u32 v178, v178, s38, 1
	v_lshl_add_u32 v179, v186, 6, v203
	v_pk_fma_f32 v[180:181], v[70:71], v[162:163], v[148:149] op_sel_hi:[1,0,1]
	s_waitcnt vmcnt(1)
	v_pk_fma_f32 v[128:129], v[128:129], v[162:163], v[142:143] op_sel_hi:[1,0,1]
	v_pk_fma_f32 v[126:127], v[126:127], v[162:163], v[140:141] op_sel_hi:[1,0,1]
	s_waitcnt vmcnt(0)
	v_pk_fma_f32 v[122:123], v[122:123], v[162:163], v[144:145] op_sel_hi:[1,0,1]
	v_add3_u32 v187, v179, s39, v178
	v_pk_fma_f32 v[178:179], v[72:73], v[162:163], v[150:151] op_sel_hi:[1,0,1]
	v_cvt_pk_f16_f32 v180, v180, v181
	v_pk_fma_f32 v[124:125], v[124:125], v[162:163], v[146:147] op_sel_hi:[1,0,1]
	v_cvt_pk_f16_f32 v126, v126, v127
	v_cvt_pk_f16_f32 v127, v128, v129
	v_cvt_pk_f16_f32 v128, v122, v123
	v_pk_fma_f32 v[184:185], v[66:67], v[162:163], v[152:153] op_sel_hi:[1,0,1]
	v_cvt_pk_f16_f32 v178, v178, v179
	v_cvt_pk_f16_f32 v129, v124, v125
	v_cmp_eq_u32_e32 vcc, 0, v186
	v_cvt_pk_f16_f32 v179, v184, v185
	v_pk_fma_f32 v[182:183], v[68:69], v[162:163], v[154:155] op_sel_hi:[1,0,1]
	v_cvt_pk_f16_f32 v181, v182, v183
	s_lshl_b32 s2, s9, 1
	s_mov_b32 s100, 2
	s_nop 1
	v_cndmask_b32_dpp v122, v126, v180, vcc quad_perm:[1,0,3,2] row_mask:0xf bank_mask:0xf
	v_cndmask_b32_dpp v123, v127, v178, vcc quad_perm:[1,0,3,2] row_mask:0xf bank_mask:0xf
	v_cndmask_b32_dpp v124, v128, v179, vcc quad_perm:[1,0,3,2] row_mask:0xf bank_mask:0xf
	v_cndmask_b32_dpp v125, v129, v181, vcc quad_perm:[1,0,3,2] row_mask:0xf bank_mask:0xf
	s_not_b64 vcc, vcc
	v_cndmask_b32_dpp v126, v180, v126, vcc quad_perm:[1,0,3,2] row_mask:0xf bank_mask:0xf
	v_cndmask_b32_dpp v127, v178, v127, vcc quad_perm:[1,0,3,2] row_mask:0xf bank_mask:0xf
	v_cndmask_b32_dpp v128, v179, v128, vcc quad_perm:[1,0,3,2] row_mask:0xf bank_mask:0xf
	v_cndmask_b32_dpp v129, v181, v129, vcc quad_perm:[1,0,3,2] row_mask:0xf bank_mask:0xf
	s_not_b64 vcc, vcc
	global_store_dwordx4 v187, v[122:125], s[36:37]
	v_pk_fma_f32 v[120:121], v[120:121], v[162:163], v[142:143] op_sel:[0,1,0]
	v_pk_fma_f32 v[118:119], v[118:119], v[162:163], v[140:141] op_sel:[0,1,0]
	v_add_u32_e32 v122, s2, v187
	s_mov_b32 s100, 2
	global_store_dwordx4 v122, v[126:129], s[36:37]
	v_pk_fma_f32 v[114:115], v[114:115], v[162:163], v[144:145] op_sel:[0,1,0]
	v_pk_fma_f32 v[124:125], v[52:53], v[162:163], v[150:151] op_sel:[0,1,0]
	v_pk_fma_f32 v[126:127], v[50:51], v[162:163], v[148:149] op_sel:[0,1,0]
	v_pk_fma_f32 v[116:117], v[116:117], v[162:163], v[146:147] op_sel:[0,1,0]
	v_cvt_pk_f16_f32 v126, v126, v127
	v_cvt_pk_f16_f32 v118, v118, v119
	v_cvt_pk_f16_f32 v119, v120, v121
	v_cvt_pk_f16_f32 v120, v114, v115
	v_pk_fma_f32 v[178:179], v[46:47], v[162:163], v[152:153] op_sel:[0,1,0]
	v_cvt_pk_f16_f32 v124, v124, v125
	v_cvt_pk_f16_f32 v121, v116, v117
	v_cvt_pk_f16_f32 v125, v178, v179
	v_pk_fma_f32 v[128:129], v[48:49], v[162:163], v[154:155] op_sel:[0,1,0]
	v_mad_u64_u32 v[122:123], s[4:5], s9, 30, v[122:123]
	v_cvt_pk_f16_f32 v127, v128, v129
	s_mov_b32 s100, 2
	s_nop 1
	v_cndmask_b32_dpp v114, v118, v126, vcc quad_perm:[1,0,3,2] row_mask:0xf bank_mask:0xf
	v_cndmask_b32_dpp v115, v119, v124, vcc quad_perm:[1,0,3,2] row_mask:0xf bank_mask:0xf
	v_cndmask_b32_dpp v116, v120, v125, vcc quad_perm:[1,0,3,2] row_mask:0xf bank_mask:0xf
	v_cndmask_b32_dpp v117, v121, v127, vcc quad_perm:[1,0,3,2] row_mask:0xf bank_mask:0xf
	s_not_b64 vcc, vcc
	v_cndmask_b32_dpp v118, v126, v118, vcc quad_perm:[1,0,3,2] row_mask:0xf bank_mask:0xf
	v_cndmask_b32_dpp v119, v124, v119, vcc quad_perm:[1,0,3,2] row_mask:0xf bank_mask:0xf
	v_cndmask_b32_dpp v120, v125, v120, vcc quad_perm:[1,0,3,2] row_mask:0xf bank_mask:0xf
	v_cndmask_b32_dpp v121, v127, v121, vcc quad_perm:[1,0,3,2] row_mask:0xf bank_mask:0xf
	s_not_b64 vcc, vcc
	global_store_dwordx4 v122, v[114:117], s[36:37]
	v_pk_fma_f32 v[112:113], v[112:113], v[160:161], v[142:143] op_sel_hi:[1,0,1]
	v_pk_fma_f32 v[110:111], v[110:111], v[160:161], v[140:141] op_sel_hi:[1,0,1]
	v_add_u32_e32 v114, s2, v122
	v_pk_fma_f32 v[116:117], v[54:55], v[160:161], v[148:149] op_sel_hi:[1,0,1]
	v_pk_fma_f32 v[106:107], v[106:107], v[160:161], v[144:145] op_sel_hi:[1,0,1]
	s_mov_b32 s100, 2
	global_store_dwordx4 v114, v[118:121], s[36:37]
	v_pk_fma_f32 v[114:115], v[56:57], v[160:161], v[150:151] op_sel_hi:[1,0,1]
	v_cvt_pk_f16_f32 v116, v116, v117
	v_pk_fma_f32 v[108:109], v[108:109], v[160:161], v[146:147] op_sel_hi:[1,0,1]
	v_cvt_pk_f16_f32 v110, v110, v111
	v_cvt_pk_f16_f32 v111, v112, v113
	v_cvt_pk_f16_f32 v112, v106, v107
	v_pk_fma_f32 v[120:121], v[42:43], v[160:161], v[152:153] op_sel_hi:[1,0,1]
	v_cvt_pk_f16_f32 v114, v114, v115
	v_cvt_pk_f16_f32 v113, v108, v109
	v_cvt_pk_f16_f32 v115, v120, v121
	v_pk_fma_f32 v[118:119], v[44:45], v[160:161], v[154:155] op_sel_hi:[1,0,1]
	v_cvt_pk_f16_f32 v117, v118, v119
	s_lshl_b32 s3, s9, 5
	v_add_u32_e32 v118, s3, v122
	s_mov_b32 s100, 2
	s_nop 1
	v_cndmask_b32_dpp v106, v110, v116, vcc quad_perm:[1,0,3,2] row_mask:0xf bank_mask:0xf
	v_cndmask_b32_dpp v107, v111, v114, vcc quad_perm:[1,0,3,2] row_mask:0xf bank_mask:0xf
	v_cndmask_b32_dpp v108, v112, v115, vcc quad_perm:[1,0,3,2] row_mask:0xf bank_mask:0xf
	v_cndmask_b32_dpp v109, v113, v117, vcc quad_perm:[1,0,3,2] row_mask:0xf bank_mask:0xf
	s_not_b64 vcc, vcc
	v_cndmask_b32_dpp v110, v116, v110, vcc quad_perm:[1,0,3,2] row_mask:0xf bank_mask:0xf
	v_cndmask_b32_dpp v111, v114, v111, vcc quad_perm:[1,0,3,2] row_mask:0xf bank_mask:0xf
	v_cndmask_b32_dpp v112, v115, v112, vcc quad_perm:[1,0,3,2] row_mask:0xf bank_mask:0xf
; __device__ __forceinline__ unsigned cvtpk_h(float lo, float hi) { f32x2 v = {lo, hi}; h16x2 b = __builtin_convertvector(v, h16x2); return __builtin_bit_cast(unsigned, b); }
; __device__ __forceinline__ void stg_line_pair(void* base, unsigned roA, unsigned rowb, const u32x4 w0, const u32x4 w1, bool odd) {
;     u32x4 a, b;
; #pragma unroll
;     for (int c = 0; c < 4; ++c) { const unsigned p1 = (unsigned)__builtin_amdgcn_update_dpp(0, (int)w1[c], 0xB1, 0xF, 0xF, false), p0 = (unsigned)__builtin_amdgcn_update_dpp(0, (int)w0[c], 0xB1, 0xF, 0xF, false);
;         a[c] = odd ? p1 : w0[c]; b[c] = odd ? w1[c] : p0; }
;     stg_u4(base, roA, a); stg_u4(base, roA + rowb, b);
; }
;     __device__ __forceinline__ void operator()(const f32x4 (&acc)[2][2][4][2], const pg8::Unit& u, int wr, int wc, int fr, int fq) const {
;     ...
;             const bool odd = (fr & 1) != 0;
;             const unsigned offA = base + ((row0 + (unsigned)(wr * 64 + (fr & ~1))) * pitch + coff) * 2u + (odd ? 64u : 0u) + 16u * fq;
; #pragma unroll
;             for (int ai = 0; ai < 2; ++ai)
; #pragma unroll
;                 for (int m = 0; m < 4; ++m) { const unsigned ro = offA + (unsigned)(ai * 8 + m) * rowstep; const float r = rs[ai][m];
;                     u32x4 w[2];
; #pragma unroll
;                     for (int bj = 0; bj < 2; ++bj) { const f32x4 v0 = acc[ai][bj][m][0] * r + bv[bj][0], v1 = acc[ai][bj][m][1] * r + bv[bj][1];
;                         w[bj].x = cvtpk_h(v0[0], v0[1]); w[bj].y = cvtpk_h(v0[2], v0[3]); w[bj].z = cvtpk_h(v1[0], v1[1]); w[bj].w = cvtpk_h(v1[2], v1[3]); }
;                     stg_line_pair(wst, ro, 2u * pitch, w[0], w[1], odd);
;                     asm volatile("" ::: "memory"); }
	v_cndmask_b32_dpp v113, v117, v113, vcc quad_perm:[1,0,3,2] row_mask:0xf bank_mask:0xf
	s_not_b64 vcc, vcc
	global_store_dwordx4 v118, v[106:109], s[36:37]
	v_pk_fma_f32 v[104:105], v[104:105], v[160:161], v[142:143] op_sel:[0,1,0]
	v_pk_fma_f32 v[102:103], v[102:103], v[160:161], v[140:141] op_sel:[0,1,0]
	v_add_u32_e32 v106, s2, v118
	v_pk_fma_f32 v[108:109], v[38:39], v[160:161], v[148:149] op_sel:[0,1,0]
	v_pk_fma_f32 v[98:99], v[98:99], v[160:161], v[144:145] op_sel:[0,1,0]
	s_mov_b32 s100, 2
	global_store_dwordx4 v106, v[110:113], s[36:37]
	v_pk_fma_f32 v[106:107], v[40:41], v[160:161], v[150:151] op_sel:[0,1,0]
	v_cvt_pk_f16_f32 v108, v108, v109
	v_pk_fma_f32 v[100:101], v[100:101], v[160:161], v[146:147] op_sel:[0,1,0]
	v_cvt_pk_f16_f32 v102, v102, v103
	v_cvt_pk_f16_f32 v103, v104, v105
	v_cvt_pk_f16_f32 v104, v98, v99
	v_pk_fma_f32 v[112:113], v[34:35], v[160:161], v[152:153] op_sel:[0,1,0]
	v_cvt_pk_f16_f32 v106, v106, v107
	v_cvt_pk_f16_f32 v105, v100, v101
	v_cvt_pk_f16_f32 v107, v112, v113
	v_pk_fma_f32 v[110:111], v[36:37], v[160:161], v[154:155] op_sel:[0,1,0]
	v_cvt_pk_f16_f32 v109, v110, v111
	v_add_u32_e32 v110, s3, v118
	s_mov_b32 s100, 2
	s_nop 1
	v_cndmask_b32_dpp v98, v102, v108, vcc quad_perm:[1,0,3,2] row_mask:0xf bank_mask:0xf
	v_cndmask_b32_dpp v99, v103, v106, vcc quad_perm:[1,0,3,2] row_mask:0xf bank_mask:0xf
	v_cndmask_b32_dpp v100, v104, v107, vcc quad_perm:[1,0,3,2] row_mask:0xf bank_mask:0xf
	v_cndmask_b32_dpp v101, v105, v109, vcc quad_perm:[1,0,3,2] row_mask:0xf bank_mask:0xf
	s_not_b64 vcc, vcc
	v_cndmask_b32_dpp v102, v108, v102, vcc quad_perm:[1,0,3,2] row_mask:0xf bank_mask:0xf
	v_cndmask_b32_dpp v103, v106, v103, vcc quad_perm:[1,0,3,2] row_mask:0xf bank_mask:0xf
	v_cndmask_b32_dpp v104, v107, v104, vcc quad_perm:[1,0,3,2] row_mask:0xf bank_mask:0xf
	v_cndmask_b32_dpp v105, v109, v105, vcc quad_perm:[1,0,3,2] row_mask:0xf bank_mask:0xf
	s_not_b64 vcc, vcc
	global_store_dwordx4 v110, v[98:101], s[36:37]
	v_pk_fma_f32 v[96:97], v[96:97], v[158:159], v[142:143] op_sel_hi:[1,0,1]
	v_pk_fma_f32 v[94:95], v[94:95], v[158:159], v[140:141] op_sel_hi:[1,0,1]
	v_add_u32_e32 v98, s2, v110
	v_pk_fma_f32 v[100:101], v[30:31], v[158:159], v[148:149] op_sel_hi:[1,0,1]
	v_pk_fma_f32 v[90:91], v[90:91], v[158:159], v[144:145] op_sel_hi:[1,0,1]
	s_mov_b32 s100, 2
	global_store_dwordx4 v98, v[102:105], s[36:37]
	v_pk_fma_f32 v[98:99], v[32:33], v[158:159], v[150:151] op_sel_hi:[1,0,1]
	v_cvt_pk_f16_f32 v100, v100, v101
	v_pk_fma_f32 v[92:93], v[92:93], v[158:159], v[146:147] op_sel_hi:[1,0,1]
	v_cvt_pk_f16_f32 v94, v94, v95
	v_cvt_pk_f16_f32 v95, v96, v97
	v_cvt_pk_f16_f32 v96, v90, v91
	v_pk_fma_f32 v[104:105], v[26:27], v[158:159], v[152:153] op_sel_hi:[1,0,1]
	v_cvt_pk_f16_f32 v98, v98, v99
	v_cvt_pk_f16_f32 v97, v92, v93
	v_cvt_pk_f16_f32 v99, v104, v105
	v_pk_fma_f32 v[102:103], v[28:29], v[158:159], v[154:155] op_sel_hi:[1,0,1]
	v_cvt_pk_f16_f32 v101, v102, v103
	s_mul_i32 s4, s9, 0xa0
	v_add_u32_e32 v102, s4, v110
	s_mov_b32 s100, 2
	s_nop 1
	v_cndmask_b32_dpp v90, v94, v100, vcc quad_perm:[1,0,3,2] row_mask:0xf bank_mask:0xf
	v_cndmask_b32_dpp v91, v95, v98, vcc quad_perm:[1,0,3,2] row_mask:0xf bank_mask:0xf
	v_cndmask_b32_dpp v92, v96, v99, vcc quad_perm:[1,0,3,2] row_mask:0xf bank_mask:0xf
	v_cndmask_b32_dpp v93, v97, v101, vcc quad_perm:[1,0,3,2] row_mask:0xf bank_mask:0xf
	s_not_b64 vcc, vcc
	v_cndmask_b32_dpp v94, v100, v94, vcc quad_perm:[1,0,3,2] row_mask:0xf bank_mask:0xf
	v_cndmask_b32_dpp v95, v98, v95, vcc quad_perm:[1,0,3,2] row_mask:0xf bank_mask:0xf
	v_cndmask_b32_dpp v96, v99, v96, vcc quad_perm:[1,0,3,2] row_mask:0xf bank_mask:0xf
	v_cndmask_b32_dpp v97, v101, v97, vcc quad_perm:[1,0,3,2] row_mask:0xf bank_mask:0xf
	s_not_b64 vcc, vcc
	global_store_dwordx4 v102, v[90:93], s[36:37]
	v_pk_fma_f32 v[88:89], v[88:89], v[158:159], v[142:143] op_sel:[0,1,0]
	v_pk_fma_f32 v[86:87], v[86:87], v[158:159], v[140:141] op_sel:[0,1,0]
	v_add_u32_e32 v90, s2, v102
	v_pk_fma_f32 v[92:93], v[22:23], v[158:159], v[148:149] op_sel:[0,1,0]
	v_pk_fma_f32 v[82:83], v[82:83], v[158:159], v[144:145] op_sel:[0,1,0]
	s_mov_b32 s100, 2
	global_store_dwordx4 v90, v[94:97], s[36:37]
	v_pk_fma_f32 v[90:91], v[24:25], v[158:159], v[150:151] op_sel:[0,1,0]
	v_cvt_pk_f16_f32 v92, v92, v93
	v_pk_fma_f32 v[84:85], v[84:85], v[158:159], v[146:147] op_sel:[0,1,0]
	v_cvt_pk_f16_f32 v86, v86, v87
	v_cvt_pk_f16_f32 v87, v88, v89
	v_cvt_pk_f16_f32 v88, v82, v83
	v_pk_fma_f32 v[96:97], v[18:19], v[158:159], v[152:153] op_sel:[0,1,0]
	v_cvt_pk_f16_f32 v90, v90, v91
	v_cvt_pk_f16_f32 v89, v84, v85
; __device__ __forceinline__ unsigned cvtpk_h(float lo, float hi) { f32x2 v = {lo, hi}; h16x2 b = __builtin_convertvector(v, h16x2); return __builtin_bit_cast(unsigned, b); }
; __device__ __forceinline__ void stg_line_pair(void* base, unsigned roA, unsigned rowb, const u32x4 w0, const u32x4 w1, bool odd) {
;     u32x4 a, b;
; #pragma unroll
;     for (int c = 0; c < 4; ++c) { const unsigned p1 = (unsigned)__builtin_amdgcn_update_dpp(0, (int)w1[c], 0xB1, 0xF, 0xF, false), p0 = (unsigned)__builtin_amdgcn_update_dpp(0, (int)w0[c], 0xB1, 0xF, 0xF, false);
;         a[c] = odd ? p1 : w0[c]; b[c] = odd ? w1[c] : p0; }
;     stg_u4(base, roA, a); stg_u4(base, roA + rowb, b);
; }
;     __device__ __forceinline__ void operator()(const f32x4 (&acc)[2][2][4][2], const pg8::Unit& u, int wr, int wc, int fr, int fq) const {
;     ...
;             const bool odd = (fr & 1) != 0;
;             const unsigned offA = base + ((row0 + (unsigned)(wr * 64 + (fr & ~1))) * pitch + coff) * 2u + (odd ? 64u : 0u) + 16u * fq;
; #pragma unroll
;             for (int ai = 0; ai < 2; ++ai)
; #pragma unroll
;                 for (int m = 0; m < 4; ++m) { const unsigned ro = offA + (unsigned)(ai * 8 + m) * rowstep; const float r = rs[ai][m];
;                     u32x4 w[2];
; #pragma unroll
;                     for (int bj = 0; bj < 2; ++bj) { const f32x4 v0 = acc[ai][bj][m][0] * r + bv[bj][0], v1 = acc[ai][bj][m][1] * r + bv[bj][1];
;                         w[bj].x = cvtpk_h(v0[0], v0[1]); w[bj].y = cvtpk_h(v0[2], v0[3]); w[bj].z = cvtpk_h(v1[0], v1[1]); w[bj].w = cvtpk_h(v1[2], v1[3]); }
;                     stg_line_pair(wst, ro, 2u * pitch, w[0], w[1], odd);
;                     asm volatile("" ::: "memory"); }
	v_cvt_pk_f16_f32 v91, v96, v97
	v_pk_fma_f32 v[94:95], v[20:21], v[158:159], v[154:155] op_sel:[0,1,0]
	v_cvt_pk_f16_f32 v93, v94, v95
	v_add_u32_e32 v94, s3, v102
	s_mov_b32 s100, 2
	s_nop 1
	v_cndmask_b32_dpp v82, v86, v92, vcc quad_perm:[1,0,3,2] row_mask:0xf bank_mask:0xf
	v_cndmask_b32_dpp v83, v87, v90, vcc quad_perm:[1,0,3,2] row_mask:0xf bank_mask:0xf
	v_cndmask_b32_dpp v84, v88, v91, vcc quad_perm:[1,0,3,2] row_mask:0xf bank_mask:0xf
	v_cndmask_b32_dpp v85, v89, v93, vcc quad_perm:[1,0,3,2] row_mask:0xf bank_mask:0xf
	s_not_b64 vcc, vcc
	v_cndmask_b32_dpp v86, v92, v86, vcc quad_perm:[1,0,3,2] row_mask:0xf bank_mask:0xf
	v_cndmask_b32_dpp v87, v90, v87, vcc quad_perm:[1,0,3,2] row_mask:0xf bank_mask:0xf
	v_cndmask_b32_dpp v88, v91, v88, vcc quad_perm:[1,0,3,2] row_mask:0xf bank_mask:0xf
	v_cndmask_b32_dpp v89, v93, v89, vcc quad_perm:[1,0,3,2] row_mask:0xf bank_mask:0xf
	s_not_b64 vcc, vcc
	global_store_dwordx4 v94, v[82:85], s[36:37]
	v_pk_fma_f32 v[80:81], v[80:81], v[156:157], v[142:143] op_sel_hi:[1,0,1]
	v_pk_fma_f32 v[78:79], v[78:79], v[156:157], v[140:141] op_sel_hi:[1,0,1]
	v_add_u32_e32 v82, s2, v94
	v_pk_fma_f32 v[84:85], v[14:15], v[156:157], v[148:149] op_sel_hi:[1,0,1]
	v_pk_fma_f32 v[74:75], v[74:75], v[156:157], v[144:145] op_sel_hi:[1,0,1]
	s_mov_b32 s100, 2
	global_store_dwordx4 v82, v[86:89], s[36:37]
	v_pk_fma_f32 v[82:83], v[16:17], v[156:157], v[150:151] op_sel_hi:[1,0,1]
	v_cvt_pk_f16_f32 v84, v84, v85
	v_pk_fma_f32 v[76:77], v[76:77], v[156:157], v[146:147] op_sel_hi:[1,0,1]
	v_cvt_pk_f16_f32 v78, v78, v79
	v_cvt_pk_f16_f32 v79, v80, v81
	v_cvt_pk_f16_f32 v80, v74, v75
	v_pk_fma_f32 v[88:89], v[10:11], v[156:157], v[152:153] op_sel_hi:[1,0,1]
	v_cvt_pk_f16_f32 v82, v82, v83
	v_cvt_pk_f16_f32 v81, v76, v77
	v_cvt_pk_f16_f32 v83, v88, v89
	v_pk_fma_f32 v[86:87], v[12:13], v[156:157], v[154:155] op_sel_hi:[1,0,1]
	v_cvt_pk_f16_f32 v85, v86, v87
	v_add_u32_e32 v86, s3, v94
	s_mov_b32 s100, 2
	s_nop 1
	v_cndmask_b32_dpp v74, v78, v84, vcc quad_perm:[1,0,3,2] row_mask:0xf bank_mask:0xf
	v_cndmask_b32_dpp v75, v79, v82, vcc quad_perm:[1,0,3,2] row_mask:0xf bank_mask:0xf
	v_cndmask_b32_dpp v76, v80, v83, vcc quad_perm:[1,0,3,2] row_mask:0xf bank_mask:0xf
	v_cndmask_b32_dpp v77, v81, v85, vcc quad_perm:[1,0,3,2] row_mask:0xf bank_mask:0xf
	s_not_b64 vcc, vcc
	v_cndmask_b32_dpp v78, v84, v78, vcc quad_perm:[1,0,3,2] row_mask:0xf bank_mask:0xf
	v_cndmask_b32_dpp v79, v82, v79, vcc quad_perm:[1,0,3,2] row_mask:0xf bank_mask:0xf
	v_cndmask_b32_dpp v80, v83, v80, vcc quad_perm:[1,0,3,2] row_mask:0xf bank_mask:0xf
	v_cndmask_b32_dpp v81, v85, v81, vcc quad_perm:[1,0,3,2] row_mask:0xf bank_mask:0xf
	s_not_b64 vcc, vcc
	global_store_dwordx4 v86, v[74:77], s[36:37]
	v_pk_fma_f32 v[64:65], v[64:65], v[156:157], v[142:143] op_sel:[0,1,0]
	v_pk_fma_f32 v[62:63], v[62:63], v[156:157], v[140:141] op_sel:[0,1,0]
	v_add_u32_e32 v74, s2, v86
	v_pk_fma_f32 v[76:77], v[6:7], v[156:157], v[148:149] op_sel:[0,1,0]
	v_pk_fma_f32 v[58:59], v[58:59], v[156:157], v[144:145] op_sel:[0,1,0]
	s_mov_b32 s100, 2
	global_store_dwordx4 v74, v[78:81], s[36:37]
	v_pk_fma_f32 v[74:75], v[8:9], v[156:157], v[150:151] op_sel:[0,1,0]
	v_cvt_pk_f16_f32 v76, v76, v77
	v_pk_fma_f32 v[60:61], v[60:61], v[156:157], v[146:147] op_sel:[0,1,0]
	v_cvt_pk_f16_f32 v62, v62, v63
	v_cvt_pk_f16_f32 v63, v64, v65
	v_cvt_pk_f16_f32 v64, v58, v59
	v_pk_fma_f32 v[80:81], v[2:3], v[156:157], v[152:153] op_sel:[0,1,0]
	v_cvt_pk_f16_f32 v74, v74, v75
	v_cvt_pk_f16_f32 v65, v60, v61
	v_cvt_pk_f16_f32 v75, v80, v81
	v_pk_fma_f32 v[78:79], v[4:5], v[156:157], v[154:155] op_sel:[0,1,0]
	v_cvt_pk_f16_f32 v77, v78, v79
	v_add_u32_e32 v78, s3, v86
	s_mov_b32 s100, 2
	s_nop 1
	v_cndmask_b32_dpp v58, v62, v76, vcc quad_perm:[1,0,3,2] row_mask:0xf bank_mask:0xf
	v_cndmask_b32_dpp v59, v63, v74, vcc quad_perm:[1,0,3,2] row_mask:0xf bank_mask:0xf
	v_cndmask_b32_dpp v60, v64, v75, vcc quad_perm:[1,0,3,2] row_mask:0xf bank_mask:0xf
	v_cndmask_b32_dpp v61, v65, v77, vcc quad_perm:[1,0,3,2] row_mask:0xf bank_mask:0xf
	s_not_b64 vcc, vcc
	v_cndmask_b32_dpp v62, v76, v62, vcc quad_perm:[1,0,3,2] row_mask:0xf bank_mask:0xf
	v_cndmask_b32_dpp v63, v74, v63, vcc quad_perm:[1,0,3,2] row_mask:0xf bank_mask:0xf
	v_cndmask_b32_dpp v64, v75, v64, vcc quad_perm:[1,0,3,2] row_mask:0xf bank_mask:0xf
	v_cndmask_b32_dpp v65, v77, v65, vcc quad_perm:[1,0,3,2] row_mask:0xf bank_mask:0xf
	s_not_b64 vcc, vcc
	global_store_dwordx4 v78, v[58:61], s[36:37]
	s_nop 1
	v_add_u32_e32 v58, s2, v78
	s_mov_b32 s100, 2
	global_store_dwordx4 v58, v[62:65], s[36:37]
	s_mov_b64 s[2:3], 0
